# G2 scan: state update of rows 64..127 deferred past the chunk barrier (KT fragments held in registers), Sb1 packed there; fills the LDS-latency bubble after the barrier
# speedup vs baseline: 1.0178x; 1.0178x over previous
.LBB0_1545:
	s_ashr_i32 s0, s42, 2
	s_and_b32 s0, s0, -8
	s_and_b32 s1, s42, 7
	s_or_b32 s0, s0, s1
	s_cmp_gt_i32 s0, 11
	s_cbranch_scc1 .LBB0_1544
	s_mul_hi_i32 s4, s0, 0x2aaaaaab
	s_lshr_b32 s1, s4, 31
	s_add_i32 s4, s4, s1
	s_mul_i32 s1, s4, 6
	s_lshr_b32 s12, s42, 3
	s_sub_i32 s5, s0, s1
	s_mov_b64 s[0:1], -1
	s_and_b64 vcc, exec, s[10:11]
	s_cbranch_vccz .LBB0_1550
	s_and_b32 s0, s12, 3
	s_waitcnt vmcnt(10)
	v_lshl_or_b32 v0, s0, 7, v126
	s_lshl_b32 s0, s5, 7
	s_ashr_i32 s1, s0, 31
	s_mul_i32 s9, s4, 0x6800000
	s_lshl_b64 s[0:1], s[0:1], 1
	s_mul_hi_i32 s8, s4, 0x6800000
	s_add_u32 s0, s0, s9
	s_addc_u32 s1, s1, s8
	v_lshrrev_b32_e32 v2, 3, v0
	v_mov_b64_e32 v[0:1], s[0:1]
	s_movk_i32 s0, 0x1a00
	v_mad_u64_u32 v[0:1], s[0:1], v2, s0, v[0:1]
	s_waitcnt vmcnt(1)
	v_lshl_add_u64 v[48:49], v[122:123], 0, v[0:1]
	v_mov_b32_e32 v0, 0
	s_mov_b32 s0, 0
	v_mov_b32_e32 v32, 0
	v_mov_b32_e32 v33, 0
	v_mov_b32_e32 v34, 0
	v_mov_b32_e32 v35, 0
	v_mov_b32_e32 v36, 0
	v_mov_b32_e32 v37, 0
	v_mov_b32_e32 v38, 0
	v_mov_b32_e32 v39, 0
	v_mov_b32_e32 v40, 0
	v_mov_b32_e32 v41, 0
	v_mov_b32_e32 v42, 0
	v_mov_b32_e32 v43, 0
	v_mov_b32_e32 v44, 0
	v_mov_b32_e32 v45, 0
	v_mov_b32_e32 v46, 0
	v_mov_b32_e32 v47, 0
	v_mov_b32_e32 v1, v0
	v_mov_b32_e32 v2, v0
	v_mov_b32_e32 v3, v0
	v_mov_b32_e32 v4, v0
	v_mov_b32_e32 v5, v0
	v_mov_b32_e32 v6, v0
	v_mov_b32_e32 v7, v0
	v_mov_b32_e32 v8, v0
	v_mov_b32_e32 v9, v0
	v_mov_b32_e32 v10, v0
	v_mov_b32_e32 v11, v0
	v_mov_b32_e32 v12, v0
	v_mov_b32_e32 v13, v0
	v_mov_b32_e32 v14, v0
	v_mov_b32_e32 v15, v0
	v_mov_b32_e32 v16, v0
	v_mov_b32_e32 v17, v0
	v_mov_b32_e32 v18, v0
	v_mov_b32_e32 v19, v0
	v_mov_b32_e32 v20, v0
	v_mov_b32_e32 v21, v0
	v_mov_b32_e32 v22, v0
	v_mov_b32_e32 v23, v0
	v_mov_b32_e32 v24, v0
	v_mov_b32_e32 v25, v0
	v_mov_b32_e32 v26, v0
	v_mov_b32_e32 v27, v0
	v_mov_b32_e32 v28, v0
	v_mov_b32_e32 v29, v0
	v_mov_b32_e32 v30, v0
	v_mov_b32_e32 v31, v0
	v_mov_b32_e32 v51, v120
	v_add_u32_e32 v50, s79, v124
	v_mov_b32_e32 v214, 0x20000
	v_mov_b32_e32 v160, 0
	v_mov_b32_e32 v161, 0
	v_mov_b32_e32 v162, 0
	v_mov_b32_e32 v163, 0
	v_mov_b32_e32 v164, 0
	v_mov_b32_e32 v165, 0
	v_mov_b32_e32 v166, 0
	v_mov_b32_e32 v167, 0
	v_mov_b32_e32 v172, 0
	v_mov_b32_e32 v173, 0
	v_mov_b32_e32 v174, 0
	v_mov_b32_e32 v175, 0
	v_mov_b32_e32 v248, 0
	v_mov_b32_e32 v249, 0
	v_mov_b32_e32 v250, 0
	v_mov_b32_e32 v251, 0
	v_mov_b32_e32 v232, 0
	v_mov_b32_e32 v233, 0
	v_mov_b32_e32 v234, 0
	v_mov_b32_e32 v235, 0
	v_mov_b32_e32 v236, 0
	v_mov_b32_e32 v237, 0
	v_mov_b32_e32 v238, 0
	v_mov_b32_e32 v239, 0
	v_mov_b32_e32 v240, 0
	v_mov_b32_e32 v241, 0
	v_mov_b32_e32 v242, 0
	v_mov_b32_e32 v243, 0
	v_mov_b32_e32 v244, 0
	v_mov_b32_e32 v245, 0
	v_mov_b32_e32 v246, 0
	v_mov_b32_e32 v247, 0
	v_mov_b32_e32 v216, 0
	v_mov_b32_e32 v217, 0
	v_mov_b32_e32 v218, 0
	v_mov_b32_e32 v219, 0
	v_mov_b32_e32 v220, 0
	v_mov_b32_e32 v221, 0
	v_mov_b32_e32 v222, 0
	v_mov_b32_e32 v223, 0
	s_waitcnt vmcnt(0)
	s_barrier
.LBB0_1548:
	ds_read_b128 v[52:55], v51 offset:0
	ds_read_b128 v[56:59], v51 offset:16384
	ds_read_b128 v[60:63], v51 offset:4096
	ds_read_b128 v[64:67], v51 offset:20480
	ds_read_b128 v[68:71], v51 offset:8192
	ds_read_b128 v[72:75], v51 offset:24576
	ds_read_b128 v[76:79], v51 offset:12288
	ds_read_b128 v[80:83], v51 offset:28672
	ds_read_b128 v[116:119], v50 offset:57344
	ds_read_b128 v[208:211], v50 offset:57360
	ds_read_b32 v212, v214
	ds_read_b128 v[84:87], v51 offset:1024
	ds_read_b128 v[88:91], v51 offset:17408
	ds_read_b128 v[92:95], v51 offset:5120
	ds_read_b128 v[96:99], v51 offset:21504
	v_mfma_f32_16x16x32_bf16 v[16:19], v[160:163], v[216:219], v[16:19]
	v_mfma_f32_16x16x32_bf16 v[16:19], v[164:167], v[220:223], v[16:19]
	v_cvt_pk_bf16_f32 v40, v8, v9
	v_mfma_f32_16x16x32_bf16 v[20:23], v[172:175], v[216:219], v[20:23]
	v_mfma_f32_16x16x32_bf16 v[20:23], v[248:251], v[220:223], v[20:23]
	v_cvt_pk_bf16_f32 v41, v10, v11
	v_mfma_f32_16x16x32_bf16 v[24:27], v[232:235], v[216:219], v[24:27]
	v_mfma_f32_16x16x32_bf16 v[24:27], v[236:239], v[220:223], v[24:27]
	v_cvt_pk_bf16_f32 v42, v12, v13
	v_mfma_f32_16x16x32_bf16 v[28:31], v[240:243], v[216:219], v[28:31]
	v_mfma_f32_16x16x32_bf16 v[28:31], v[244:247], v[220:223], v[28:31]
	v_cvt_pk_bf16_f32 v43, v14, v15
	s_waitcnt lgkmcnt(14)
	v_mfma_f32_16x16x32_bf16 v[176:179], v[52:55], v[44:47], 0
	ds_read_b128 v[100:103], v51 offset:9216
	s_waitcnt lgkmcnt(14)
	v_mfma_f32_16x16x32_bf16 v[192:195], v[56:59], v[44:47], 0
	ds_read_b128 v[104:107], v51 offset:25600
	s_waitcnt lgkmcnt(14)
	v_mfma_f32_16x16x32_bf16 v[180:183], v[60:63], v[44:47], 0
	ds_read_b128 v[108:111], v51 offset:13312
	v_cvt_pk_bf16_f32 v36, v16, v17
	v_cvt_pk_bf16_f32 v37, v18, v19
	s_waitcnt lgkmcnt(14)
	v_mfma_f32_16x16x32_bf16 v[196:199], v[64:67], v[44:47], 0
	ds_read_b128 v[112:115], v51 offset:29696
	v_cvt_pk_bf16_f32 v38, v20, v21
	v_cvt_pk_bf16_f32 v39, v22, v23
	s_waitcnt lgkmcnt(14)
	v_mfma_f32_16x16x32_bf16 v[184:187], v[68:71], v[44:47], 0
	v_cvt_pk_bf16_f32 v32, v24, v25
	v_cvt_pk_bf16_f32 v33, v26, v27
	s_waitcnt lgkmcnt(13)
	v_mfma_f32_16x16x32_bf16 v[200:203], v[72:75], v[44:47], 0
	v_cvt_pk_bf16_f32 v34, v28, v29
	v_cvt_pk_bf16_f32 v35, v30, v31
	s_waitcnt lgkmcnt(12)
	v_mfma_f32_16x16x32_bf16 v[188:191], v[76:79], v[44:47], 0
	s_waitcnt lgkmcnt(10)
	v_lshlrev_b32_e32 v232, 16, v116
	v_and_b32_e32 v233, 0xffff0000, v116
	v_mfma_f32_16x16x32_bf16 v[204:207], v[80:83], v[44:47], 0
	v_lshlrev_b32_e32 v234, 16, v117
	v_and_b32_e32 v235, 0xffff0000, v117
	ds_read_b128 v[128:131], v51 offset:2048
	ds_read_b128 v[132:135], v51 offset:18432
	ds_read_b128 v[136:139], v51 offset:6144
	ds_read_b128 v[140:143], v51 offset:22528
	s_waitcnt lgkmcnt(11)
	v_mfma_f32_16x16x32_bf16 v[176:179], v[84:87], v[40:43], v[176:179]
	ds_read_b128 v[144:147], v51 offset:10240
	v_lshlrev_b32_e32 v236, 16, v118
	v_and_b32_e32 v237, 0xffff0000, v118
	s_waitcnt lgkmcnt(11)
	v_mfma_f32_16x16x32_bf16 v[192:195], v[88:91], v[40:43], v[192:195]
	ds_read_b128 v[148:151], v51 offset:26624
	v_lshlrev_b32_e32 v238, 16, v119
	v_and_b32_e32 v239, 0xffff0000, v119
	s_waitcnt lgkmcnt(11)
	v_mfma_f32_16x16x32_bf16 v[180:183], v[92:95], v[40:43], v[180:183]
	ds_read_b128 v[152:155], v51 offset:14336
	v_lshlrev_b32_e32 v240, 16, v208
	v_and_b32_e32 v241, 0xffff0000, v208
	s_waitcnt lgkmcnt(11)
	v_mfma_f32_16x16x32_bf16 v[196:199], v[96:99], v[40:43], v[196:199]
	ds_read_b128 v[156:159], v51 offset:30720
	v_lshlrev_b32_e32 v242, 16, v209
	v_and_b32_e32 v243, 0xffff0000, v209
	s_waitcnt lgkmcnt(11)
	v_mfma_f32_16x16x32_bf16 v[184:187], v[100:103], v[40:43], v[184:187]
	v_lshlrev_b32_e32 v244, 16, v210
	v_and_b32_e32 v245, 0xffff0000, v210
	s_waitcnt lgkmcnt(10)
	v_mfma_f32_16x16x32_bf16 v[200:203], v[104:107], v[40:43], v[200:203]
	v_lshlrev_b32_e32 v246, 16, v211
	v_and_b32_e32 v247, 0xffff0000, v211
	s_waitcnt lgkmcnt(9)
	v_mfma_f32_16x16x32_bf16 v[188:191], v[108:111], v[40:43], v[188:191]
	v_mul_f32_e32 v0, v212, v0
	v_mul_f32_e32 v1, v212, v1
	s_waitcnt lgkmcnt(8)
	v_mfma_f32_16x16x32_bf16 v[204:207], v[112:115], v[40:43], v[204:207]
	v_mul_f32_e32 v2, v212, v2
	v_mul_f32_e32 v3, v212, v3
	ds_read_b128 v[52:55], v51 offset:3072
	ds_read_b128 v[56:59], v51 offset:7168
	ds_read_b128 v[60:63], v51 offset:11264
	ds_read_b128 v[64:67], v51 offset:15360
	s_waitcnt lgkmcnt(11)
	v_mfma_f32_16x16x32_bf16 v[176:179], v[128:131], v[36:39], v[176:179]
	ds_read_b128 v[68:71], v51 offset:19456
	v_mul_f32_e32 v4, v212, v4
	v_mul_f32_e32 v5, v212, v5
	s_waitcnt lgkmcnt(11)
	v_mfma_f32_16x16x32_bf16 v[192:195], v[132:135], v[36:39], v[192:195]
	ds_read_b128 v[72:75], v51 offset:23552
	v_mul_f32_e32 v6, v212, v6
	v_mul_f32_e32 v7, v212, v7
	s_waitcnt lgkmcnt(11)
	v_mfma_f32_16x16x32_bf16 v[180:183], v[136:139], v[36:39], v[180:183]
	ds_read_b128 v[76:79], v51 offset:27648
	v_mul_f32_e32 v8, v212, v8
	v_mul_f32_e32 v9, v212, v9
	s_waitcnt lgkmcnt(11)
	v_mfma_f32_16x16x32_bf16 v[196:199], v[140:143], v[36:39], v[196:199]
	ds_read_b128 v[80:83], v51 offset:31744
	v_mul_f32_e32 v10, v212, v10
	v_mul_f32_e32 v11, v212, v11
	s_waitcnt lgkmcnt(11)
	v_mfma_f32_16x16x32_bf16 v[184:187], v[144:147], v[36:39], v[184:187]
	v_mul_f32_e32 v12, v212, v12
	v_mul_f32_e32 v13, v212, v13
	s_waitcnt lgkmcnt(10)
	v_mfma_f32_16x16x32_bf16 v[200:203], v[148:151], v[36:39], v[200:203]
	v_mul_f32_e32 v14, v212, v14
	v_mul_f32_e32 v15, v212, v15
	s_waitcnt lgkmcnt(9)
	v_mfma_f32_16x16x32_bf16 v[188:191], v[152:155], v[36:39], v[188:191]
	v_mul_f32_e32 v16, v212, v16
	v_mul_f32_e32 v17, v212, v17
	s_waitcnt lgkmcnt(8)
	v_mfma_f32_16x16x32_bf16 v[204:207], v[156:159], v[36:39], v[204:207]
	v_mul_f32_e32 v18, v212, v18
	v_mul_f32_e32 v19, v212, v19
	ds_read_b128 v[84:87], v51 offset:49152
	ds_read_b128 v[88:91], v51 offset:51200
	ds_read_b128 v[92:95], v51 offset:53248
	ds_read_b128 v[96:99], v51 offset:55296
	s_waitcnt lgkmcnt(11)
	v_mfma_f32_16x16x32_bf16 v[176:179], v[52:55], v[32:35], v[176:179]
	ds_read_b128 v[100:103], v51 offset:50176
	v_mul_f32_e32 v20, v212, v20
	v_mul_f32_e32 v21, v212, v21
	v_mul_f32_e32 v22, v212, v22
	s_waitcnt lgkmcnt(11)
	v_mfma_f32_16x16x32_bf16 v[180:183], v[56:59], v[32:35], v[180:183]
	ds_read_b128 v[104:107], v51 offset:52224
	v_mul_f32_e32 v23, v212, v23
	v_mul_f32_e32 v24, v212, v24
	v_mul_f32_e32 v25, v212, v25
	s_waitcnt lgkmcnt(11)
	v_mfma_f32_16x16x32_bf16 v[184:187], v[60:63], v[32:35], v[184:187]
	ds_read_b128 v[108:111], v51 offset:54272
	v_mul_f32_e32 v26, v212, v26
	v_mul_f32_e32 v27, v212, v27
	v_mul_f32_e32 v28, v212, v28
	s_waitcnt lgkmcnt(11)
	v_mfma_f32_16x16x32_bf16 v[188:191], v[64:67], v[32:35], v[188:191]
	ds_read_b128 v[112:115], v51 offset:56320
	v_mul_f32_e32 v29, v212, v29
	v_mul_f32_e32 v30, v212, v30
	v_mul_f32_e32 v31, v212, v31
	s_waitcnt lgkmcnt(11)
	v_mfma_f32_16x16x32_bf16 v[192:195], v[68:71], v[32:35], v[192:195]
	v_sub_f32_e32 v232, v232, v176
	v_sub_f32_e32 v233, v233, v177
	v_sub_f32_e32 v234, v234, v178
	v_sub_f32_e32 v235, v235, v179
	s_waitcnt lgkmcnt(10)
	v_mfma_f32_16x16x32_bf16 v[196:199], v[72:75], v[32:35], v[196:199]
	v_sub_f32_e32 v236, v236, v180
	v_sub_f32_e32 v237, v237, v181
	v_sub_f32_e32 v238, v238, v182
	v_sub_f32_e32 v239, v239, v183
	s_waitcnt lgkmcnt(9)
	v_mfma_f32_16x16x32_bf16 v[200:203], v[76:79], v[32:35], v[200:203]
	v_cvt_pk_bf16_f32 v216, v232, v233
	v_cvt_pk_bf16_f32 v217, v234, v235
	v_cvt_pk_bf16_f32 v218, v236, v237
	v_cvt_pk_bf16_f32 v219, v238, v239
	s_waitcnt lgkmcnt(8)
	v_mfma_f32_16x16x32_bf16 v[204:207], v[80:83], v[32:35], v[204:207]
	v_sub_f32_e32 v240, v240, v184
	v_sub_f32_e32 v241, v241, v185
	v_sub_f32_e32 v242, v242, v186
	v_sub_f32_e32 v243, v243, v187
	v_sub_f32_e32 v244, v244, v188
	v_sub_f32_e32 v245, v245, v189
	v_sub_f32_e32 v246, v246, v190
	v_sub_f32_e32 v247, v247, v191
	ds_read_b128 v[128:131], v51 offset:32768
	ds_read_b128 v[132:135], v51 offset:33792
	ds_read_b128 v[136:139], v51 offset:34816
	ds_read_b128 v[140:143], v51 offset:35840
	ds_read_b128 v[144:147], v51 offset:36864
	ds_read_b128 v[148:151], v51 offset:37888
	s_waitcnt lgkmcnt(13)
	v_mfma_f32_16x16x32_bf16 v[192:195], v[84:87], v[216:219], v[192:195]
	v_cvt_pk_bf16_f32 v220, v240, v241
	v_cvt_pk_bf16_f32 v221, v242, v243
	s_waitcnt lgkmcnt(12)
	v_mfma_f32_16x16x32_bf16 v[196:199], v[88:91], v[216:219], v[196:199]
	v_cvt_pk_bf16_f32 v222, v244, v245
	v_cvt_pk_bf16_f32 v223, v246, v247
	s_waitcnt lgkmcnt(11)
	v_mfma_f32_16x16x32_bf16 v[200:203], v[92:95], v[216:219], v[200:203]
	ds_read_b128 v[152:155], v51 offset:38912
	s_waitcnt lgkmcnt(11)
	v_mfma_f32_16x16x32_bf16 v[204:207], v[96:99], v[216:219], v[204:207]
	ds_read_b128 v[156:159], v51 offset:39936
	s_waitcnt lgkmcnt(11)
	v_mfma_f32_16x16x32_bf16 v[192:195], v[100:103], v[220:223], v[192:195]
	s_waitcnt lgkmcnt(10)
	v_mfma_f32_16x16x32_bf16 v[196:199], v[104:107], v[220:223], v[196:199]
	s_waitcnt lgkmcnt(9)
	v_mfma_f32_16x16x32_bf16 v[200:203], v[108:111], v[220:223], v[200:203]
	s_waitcnt lgkmcnt(8)
	v_mfma_f32_16x16x32_bf16 v[204:207], v[112:115], v[220:223], v[204:207]
	ds_read_b128 v[160:163], v51 offset:40960
	ds_read_b128 v[164:167], v51 offset:41984
	ds_read_b128 v[172:175], v51 offset:43008
	ds_read_b128 v[248:251], v51 offset:44032
	ds_read_b128 v[232:235], v51 offset:45056
	ds_read_b128 v[236:239], v51 offset:46080
	ds_read_b128 v[240:243], v51 offset:47104
	s_add_i32 s0, s0, 1
	s_and_b32 s1, s0, 1
	s_lshl_b32 s8, s1, 16
	s_lshl_b32 s1, s1, 2
	s_add_i32 s9, s8, s79
	s_add_i32 s1, s1, 0x20000
	s_waitcnt lgkmcnt(14)
	v_mfma_f32_16x16x32_bf16 v[0:3], v[128:131], v[216:219], v[0:3]
	ds_read_b128 v[244:247], v51 offset:48128
	s_waitcnt lgkmcnt(14)
	v_mfma_f32_16x16x32_bf16 v[0:3], v[132:135], v[220:223], v[0:3]
	v_add_u32_e32 v50, s9, v124
	v_mov_b32_e32 v214, s1
	s_waitcnt lgkmcnt(13)
	v_mfma_f32_16x16x32_bf16 v[4:7], v[136:139], v[216:219], v[4:7]
	s_waitcnt lgkmcnt(12)
	v_mfma_f32_16x16x32_bf16 v[4:7], v[140:143], v[220:223], v[4:7]
	v_cvt_pk_bf16_f32 v224, v192, v193
	v_cvt_pk_bf16_f32 v225, v194, v195
	v_cvt_pk_bf16_f32 v226, v196, v197
	v_cvt_pk_bf16_f32 v227, v198, v199
	s_waitcnt lgkmcnt(11)
	v_mfma_f32_16x16x32_bf16 v[8:11], v[144:147], v[216:219], v[8:11]
	s_waitcnt lgkmcnt(10)
	v_mfma_f32_16x16x32_bf16 v[8:11], v[148:151], v[220:223], v[8:11]
	v_cvt_pk_bf16_f32 v228, v200, v201
	v_cvt_pk_bf16_f32 v229, v202, v203
	v_cvt_pk_bf16_f32 v230, v204, v205
	v_cvt_pk_bf16_f32 v231, v206, v207
	global_store_dwordx4 v[48:49], v[224:227], off
	s_waitcnt lgkmcnt(9)
	v_mfma_f32_16x16x32_bf16 v[12:15], v[152:155], v[216:219], v[12:15]
	v_cvt_pk_bf16_f32 v44, v0, v1
	v_cvt_pk_bf16_f32 v45, v2, v3
	v_cvt_pk_bf16_f32 v46, v4, v5
	v_cvt_pk_bf16_f32 v47, v6, v7
	global_store_dwordx4 v[48:49], v[228:231], off offset:16
	v_add_u32_e32 v51, s8, v120
	s_mov_b64 s[8:9], 0x68000
	v_lshl_add_u64 v[48:49], v[48:49], 0, s[8:9]
	s_cmpk_lg_i32 s0, 0x100
	s_waitcnt lgkmcnt(0)
	v_mfma_f32_16x16x32_bf16 v[12:15], v[156:159], v[220:223], v[12:15]
	s_barrier
	s_cbranch_scc1 .LBB0_1548
	s_mov_b64 s[0:1], 0
